# attention: cross-half row max via v_permlane32_swap (VALU) instead of ds_bpermute + lgkmcnt(0) round trip
# speedup vs baseline: 1.0303x; 1.0064x over previous
; #define MAX3(a, b, c) ({ float r_; asm("v_max3_f32 %0, %1, %2, %3" : "=v"(r_) : "v"(a), "v"(b), "v"(c)); r_; })
; __device__ __forceinline__ void unit(LAS unsigned char* lds, const bf16* __restrict__ Q, const bf16* __restrict__ Kn, const bf16* __restrict__ Kr, const bf16* __restrict__ Vt, bf16* __restrict__ O,
;                                      int tokbase, int S, int h, int qb, const int tid) {
;     ...
;         float mx = MAX3(p0[0], p0[1], p0[2]);
;         mx = MAX3(mx, p0[3], p0[4]); mx = MAX3(mx, p0[5], p0[6]); mx = MAX3(mx, p0[7], p0[8]); mx = MAX3(mx, p0[9], p0[10]); mx = MAX3(mx, p0[11], p0[12]);
;         mx = MAX3(mx, p0[13], p0[14]); mx = MAX3(mx, p0[15], p1[0]); mx = MAX3(mx, p1[1], p1[2]); mx = MAX3(mx, p1[3], p1[4]); mx = MAX3(mx, p1[5], p1[6]);
;         mx = MAX3(mx, p1[7], p1[8]); mx = MAX3(mx, p1[9], p1[10]); mx = MAX3(mx, p1[11], p1[12]); mx = MAX3(mx, p1[13], p1[14]); mx = MAX3(mx, p1[15], p1[15]);
;         { const float mo = __shfl_xor(mx, 32); mx = MAX3(mx, mo, mo); }
;         if (__any(mx - mref > 8.0f)) {
.LBB0_729:
	s_or_b64 exec, exec, s[26:27]
	global_load_dwordx4 v[126:129], v[162:163], off
	s_and_b32 s37, 1, s36
	s_cselect_b32 s26, 0, 0x5800
	s_add_i32 s45, s26, 0
	v_add3_u32 v42, s45, v168, v169
	ds_read_b128 v[34:37], v42
	ds_read_b128 v[66:69], v42 offset:32
	ds_read_b128 v[38:41], v42 offset:6656
	ds_read_b128 v[70:73], v42 offset:6688
	ds_read_b128 v[74:77], v42 offset:64
	ds_read_b128 v[78:81], v42 offset:96
	ds_read_b128 v[82:85], v42 offset:6720
	ds_read_b128 v[86:89], v42 offset:6752
	ds_read_b128 v[90:93], v42 offset:128
	ds_read_b128 v[94:97], v42 offset:160
	ds_read_b128 v[174:177], v42 offset:6784
	ds_read_b128 v[182:185], v42 offset:6816
	s_waitcnt lgkmcnt(11)
	v_mfma_f32_32x32x16_bf16 v[50:65], v[34:37], v[118:121], 0
	s_waitcnt lgkmcnt(9)
	v_mfma_f32_32x32x16_bf16 v[34:49], v[38:41], v[118:121], 0
	v_mfma_f32_32x32x16_bf16 v[50:65], v[66:69], v[114:117], v[50:65]
	v_and_b32_e32 v68, 64, v238
	v_xor_b32_e32 v67, 32, v238
	v_add_u32_e32 v68, 64, v68
	v_cmp_lt_i32_e32 vcc, v67, v68
	s_nop 1
	v_cndmask_b32_e32 v67, v238, v67, vcc
	s_waitcnt lgkmcnt(8)
	v_mfma_f32_32x32x16_bf16 v[34:49], v[70:73], v[114:117], v[34:49]
	v_lshlrev_b32_e32 v155, 2, v67
	s_waitcnt lgkmcnt(7)
	v_mfma_f32_32x32x16_bf16 v[50:65], v[74:77], v[110:113], v[50:65]
	s_waitcnt lgkmcnt(5)
	v_mfma_f32_32x32x16_bf16 v[34:49], v[82:85], v[110:113], v[34:49]
	v_mfma_f32_32x32x16_bf16 v[50:65], v[78:81], v[106:109], v[50:65]
	s_waitcnt lgkmcnt(4)
	v_mfma_f32_32x32x16_bf16 v[34:49], v[86:89], v[106:109], v[34:49]
	s_waitcnt lgkmcnt(3)
	v_mfma_f32_32x32x16_bf16 v[50:65], v[90:93], v[102:105], v[50:65]
	s_waitcnt lgkmcnt(1)
	v_mfma_f32_32x32x16_bf16 v[34:49], v[174:177], v[102:105], v[34:49]
	v_mfma_f32_32x32x16_bf16 v[50:65], v[94:97], v[98:101], v[50:65]
	v_max3_f32 v66, v50, v51, v52
	s_nop 0
	v_max3_f32 v66, v66, v53, v54
	s_nop 0
	v_max3_f32 v66, v66, v55, v56
	s_nop 0
	v_max3_f32 v66, v66, v57, v58
	s_waitcnt lgkmcnt(0)
	v_mfma_f32_32x32x16_bf16 v[34:49], v[182:185], v[98:101], v[34:49]
	v_max3_f32 v66, v66, v59, v60
	s_nop 0
	v_max3_f32 v66, v66, v61, v62
	s_nop 0
	v_max3_f32 v66, v66, v63, v64
	s_nop 0
	v_max3_f32 v66, v66, v65, v34
	s_nop 0
	v_max3_f32 v66, v66, v35, v36
	s_nop 0
	v_max3_f32 v66, v66, v37, v38
	s_nop 0
	v_max3_f32 v66, v66, v39, v40
	s_nop 0
	v_max3_f32 v66, v66, v41, v42
	s_nop 0
	v_max3_f32 v66, v66, v43, v44
	s_nop 0
	v_max3_f32 v66, v66, v45, v46
	s_nop 0
	v_max3_f32 v66, v66, v47, v48
	s_nop 0
	v_max3_f32 v66, v66, v49, v49
	v_mov_b32_e32 v67, v66
	s_nop 1
	v_permlane32_swap_b32_e32 v67, v66
	v_max_f32_e32 v66, v66, v67
	s_nop 0
	v_sub_f32_e32 v66, v66, v157
	v_cmp_lt_f32_e32 vcc, s87, v66
	s_cbranch_vccz .LBB0_731
	v_max_f32_e32 v66, v66, v66
	v_max_f32_e32 v67, 0, v66
	v_exp_f32_e64 v66, -v67
	v_add_f32_e32 v157, v157, v67
	v_pk_mul_f32 v[16:17], v[16:17], v[66:67] op_sel_hi:[1,0]
	v_pk_mul_f32 v[14:15], v[14:15], v[66:67] op_sel_hi:[1,0]
	v_pk_mul_f32 v[12:13], v[12:13], v[66:67] op_sel_hi:[1,0]
	v_pk_mul_f32 v[10:11], v[10:11], v[66:67] op_sel_hi:[1,0]
	v_pk_mul_f32 v[8:9], v[8:9], v[66:67] op_sel_hi:[1,0]
	v_pk_mul_f32 v[6:7], v[6:7], v[66:67] op_sel_hi:[1,0]
	v_pk_mul_f32 v[4:5], v[4:5], v[66:67] op_sel_hi:[1,0]
	v_pk_mul_f32 v[2:3], v[2:3], v[66:67] op_sel_hi:[1,0]
	v_pk_mul_f32 v[32:33], v[32:33], v[66:67] op_sel_hi:[1,0]
	v_pk_mul_f32 v[30:31], v[30:31], v[66:67] op_sel_hi:[1,0]
	v_pk_mul_f32 v[28:29], v[28:29], v[66:67] op_sel_hi:[1,0]
	v_pk_mul_f32 v[26:27], v[26:27], v[66:67] op_sel_hi:[1,0]
	v_pk_mul_f32 v[24:25], v[24:25], v[66:67] op_sel_hi:[1,0]
	v_pk_mul_f32 v[22:23], v[22:23], v[66:67] op_sel_hi:[1,0]
	v_pk_mul_f32 v[20:21], v[20:21], v[66:67] op_sel_hi:[1,0]
	v_pk_mul_f32 v[18:19], v[18:19], v[66:67] op_sel_hi:[1,0]
	v_mul_f32_e32 v153, v153, v66

; #define LAS __attribute__((address_space(3)))
; #define MAX3(a, b, c) ({ float r_; asm("v_max3_f32 %0, %1, %2, %3" : "=v"(r_) : "v"(a), "v"(b), "v"(c)); r_; })
; __device__ __forceinline__ void unit(LAS unsigned char* lds, const bf16* __restrict__ Q, const bf16* __restrict__ Kn, const bf16* __restrict__ Kr, const bf16* __restrict__ Vt, bf16* __restrict__ O,
;                                      int tokbase, int S, int h, int qb, const int tid) {
;     ...
;         const LAS unsigned char* kb = lds + (t & 1) * BUFB;
;         const LAS unsigned char* vb = kb + KBYTES;
;         f32x16 p0 = {}, p1 = {};
;         {
;             bf16x8 kf0[6], kf1[6];
; #pragma unroll
;             for (int d0 = 0; d0 < 6; ++d0) { kf0[d0] = *(const LAS bf16x8*)(kb + r32 * KSTR + d0 * 32 + hi * 16); kf1[d0] = *(const LAS bf16x8*)(kb + (32 + r32) * KSTR + d0 * 32 + hi * 16); }
;             __builtin_amdgcn_sched_barrier(0);
; #pragma unroll
;             for (int d0 = 0; d0 < 6; ++d0) { p0 = __builtin_amdgcn_mfma_f32_32x32x16_bf16(kf0[d0], qf[d0], p0, 0, 0, 0); p1 = __builtin_amdgcn_mfma_f32_32x32x16_bf16(kf1[d0], qf[d0], p1, 0, 0, 0); }
;         }
;         float mx = MAX3(p0[0], p0[1], p0[2]);
;         mx = MAX3(mx, p0[3], p0[4]); mx = MAX3(mx, p0[5], p0[6]); mx = MAX3(mx, p0[7], p0[8]); mx = MAX3(mx, p0[9], p0[10]); mx = MAX3(mx, p0[11], p0[12]);
;         mx = MAX3(mx, p0[13], p0[14]); mx = MAX3(mx, p0[15], p1[0]); mx = MAX3(mx, p1[1], p1[2]); mx = MAX3(mx, p1[3], p1[4]); mx = MAX3(mx, p1[5], p1[6]);
;         mx = MAX3(mx, p1[7], p1[8]); mx = MAX3(mx, p1[9], p1[10]); mx = MAX3(mx, p1[11], p1[12]); mx = MAX3(mx, p1[13], p1[14]); mx = MAX3(mx, p1[15], p1[15]);
;         { const float mo = __shfl_xor(mx, 32); mx = MAX3(mx, mo, mo); }
;         if (__any(mx - mref > 8.0f)) {
.LBB0_737:
	v_add3_u32 v42, s37, v168, v169
	ds_read_b128 v[34:37], v42
	ds_read_b128 v[66:69], v42 offset:32
	ds_read_b128 v[38:41], v42 offset:6656
	ds_read_b128 v[70:73], v42 offset:6688
	ds_read_b128 v[74:77], v42 offset:64
	ds_read_b128 v[78:81], v42 offset:96
	ds_read_b128 v[82:85], v42 offset:6720
	ds_read_b128 v[86:89], v42 offset:6752
	ds_read_b128 v[90:93], v42 offset:128
	ds_read_b128 v[94:97], v42 offset:160
	ds_read_b128 v[122:125], v42 offset:6784
	ds_read_b128 v[126:129], v42 offset:6816
	s_waitcnt lgkmcnt(11)
	v_mfma_f32_32x32x16_bf16 v[50:65], v[34:37], v[118:121], 0
	s_waitcnt lgkmcnt(9)
	v_mfma_f32_32x32x16_bf16 v[34:49], v[38:41], v[118:121], 0
	v_mfma_f32_32x32x16_bf16 v[50:65], v[66:69], v[114:117], v[50:65]
	s_waitcnt lgkmcnt(8)
	v_mfma_f32_32x32x16_bf16 v[34:49], v[70:73], v[114:117], v[34:49]
	s_waitcnt lgkmcnt(7)
	v_mfma_f32_32x32x16_bf16 v[50:65], v[74:77], v[110:113], v[50:65]
	s_waitcnt lgkmcnt(5)
	v_mfma_f32_32x32x16_bf16 v[34:49], v[82:85], v[110:113], v[34:49]
	v_mfma_f32_32x32x16_bf16 v[50:65], v[78:81], v[106:109], v[50:65]
	s_waitcnt lgkmcnt(4)
	v_mfma_f32_32x32x16_bf16 v[34:49], v[86:89], v[106:109], v[34:49]
	s_waitcnt lgkmcnt(3)
	v_mfma_f32_32x32x16_bf16 v[50:65], v[90:93], v[102:105], v[50:65]
	s_waitcnt lgkmcnt(1)
	v_mfma_f32_32x32x16_bf16 v[34:49], v[122:125], v[102:105], v[34:49]
	v_mfma_f32_32x32x16_bf16 v[50:65], v[94:97], v[98:101], v[50:65]
	v_max3_f32 v66, v50, v51, v52
	s_nop 0
	v_max3_f32 v66, v66, v53, v54
	s_nop 0
	v_max3_f32 v66, v66, v55, v56
	s_nop 0
	v_max3_f32 v66, v66, v57, v58
	s_waitcnt lgkmcnt(0)
	v_mfma_f32_32x32x16_bf16 v[34:49], v[126:129], v[98:101], v[34:49]
	v_max3_f32 v66, v66, v59, v60
	s_nop 0
	v_max3_f32 v66, v66, v61, v62
	s_nop 0
	v_max3_f32 v66, v66, v63, v64
	s_nop 0
	v_max3_f32 v66, v66, v65, v34
	s_nop 0
	v_max3_f32 v66, v66, v35, v36
	s_nop 0
	v_max3_f32 v66, v66, v37, v38
	s_nop 0
	v_max3_f32 v66, v66, v39, v40
	s_nop 0
	v_max3_f32 v66, v66, v41, v42
	s_nop 0
	v_max3_f32 v66, v66, v43, v44
	s_nop 0
	v_max3_f32 v66, v66, v45, v46
	s_nop 0
	v_max3_f32 v66, v66, v47, v48
	s_nop 0
	v_max3_f32 v66, v66, v49, v49
	v_mov_b32_e32 v67, v66
	s_nop 1
	v_permlane32_swap_b32_e32 v67, v66
	v_max_f32_e32 v66, v66, v67
	s_nop 0
	v_sub_f32_e32 v66, v66, v157
	v_cmp_lt_f32_e32 vcc, s87, v66
	s_cbranch_vccz .LBB0_739
	v_max_f32_e32 v66, v66, v66
	v_max_f32_e32 v67, 0, v66
	v_exp_f32_e64 v66, -v67
	v_add_f32_e32 v157, v157, v67
	v_pk_mul_f32 v[16:17], v[16:17], v[66:67] op_sel_hi:[1,0]
	v_pk_mul_f32 v[14:15], v[14:15], v[66:67] op_sel_hi:[1,0]
	v_pk_mul_f32 v[12:13], v[12:13], v[66:67] op_sel_hi:[1,0]
	v_pk_mul_f32 v[10:11], v[10:11], v[66:67] op_sel_hi:[1,0]
	v_pk_mul_f32 v[8:9], v[8:9], v[66:67] op_sel_hi:[1,0]
	v_pk_mul_f32 v[6:7], v[6:7], v[66:67] op_sel_hi:[1,0]
	v_pk_mul_f32 v[4:5], v[4:5], v[66:67] op_sel_hi:[1,0]
	v_pk_mul_f32 v[2:3], v[2:3], v[66:67] op_sel_hi:[1,0]
	v_pk_mul_f32 v[32:33], v[32:33], v[66:67] op_sel_hi:[1,0]
	v_pk_mul_f32 v[30:31], v[30:31], v[66:67] op_sel_hi:[1,0]
	v_pk_mul_f32 v[28:29], v[28:29], v[66:67] op_sel_hi:[1,0]
	v_pk_mul_f32 v[26:27], v[26:27], v[66:67] op_sel_hi:[1,0]
	v_pk_mul_f32 v[24:25], v[24:25], v[66:67] op_sel_hi:[1,0]
	v_pk_mul_f32 v[22:23], v[22:23], v[66:67] op_sel_hi:[1,0]
	v_pk_mul_f32 v[20:21], v[20:21], v[66:67] op_sel_hi:[1,0]
	v_pk_mul_f32 v[18:19], v[18:19], v[66:67] op_sel_hi:[1,0]
	v_mul_f32_e32 v153, v153, v66
